# v36 + static s_setprio 1 for waves 4-7 at attention item-loop heads
# baseline (speedup 1.0000x reference)
.LBB0_309:
	v_readfirstlane_b32 s101, v147
	s_nop 0
	s_bitcmp1_b32 s101, 8
	s_cbranch_scc0 .Lprio_skip_309
	s_setprio 1
